# XCD-local barriers after norm / SwiGLU / attention no longer invalidate L1 (each workgroup already invalidated at the preceding counter wait or grid sync and read none of the consumed rows since)
# baseline (speedup 1.0000x reference)
; DI void grid_barrier(unsigned* cnt, unsigned target) {
;     asm volatile("s_waitcnt vmcnt(0) lgkmcnt(0)" ::: "memory");
;     __syncthreads();
;     if (threadIdx.x == 0) {
;         __builtin_amdgcn_fence(__ATOMIC_RELEASE, "agent");
;         asm volatile("s_waitcnt vmcnt(0)" ::: "memory");
;         __hip_atomic_fetch_add(cnt, 1u, __ATOMIC_RELAXED, __HIP_MEMORY_SCOPE_AGENT);
;         while (__hip_atomic_load(cnt, __ATOMIC_RELAXED, __HIP_MEMORY_SCOPE_AGENT) < target) __builtin_amdgcn_s_sleep(2);
;         __builtin_amdgcn_fence(__ATOMIC_ACQUIRE, "agent");
;         asm volatile("s_waitcnt vmcnt(0)" ::: "memory");
;     }
;     __syncthreads();
; }
.Lli_Y:
.Llb_Y:
	s_mov_b64 exec, s[4:5]
	s_barrier
	s_mov_b32 s98, 3
	s_branch .LBB0_585

; DI void grid_barrier(unsigned* cnt, unsigned target) {
;     asm volatile("s_waitcnt vmcnt(0) lgkmcnt(0)" ::: "memory");
;     __syncthreads();
;     if (threadIdx.x == 0) {
;         __builtin_amdgcn_fence(__ATOMIC_RELEASE, "agent");
;         asm volatile("s_waitcnt vmcnt(0)" ::: "memory");
;         __hip_atomic_fetch_add(cnt, 1u, __ATOMIC_RELAXED, __HIP_MEMORY_SCOPE_AGENT);
;         while (__hip_atomic_load(cnt, __ATOMIC_RELAXED, __HIP_MEMORY_SCOPE_AGENT) < target) __builtin_amdgcn_s_sleep(2);
;         __builtin_amdgcn_fence(__ATOMIC_ACQUIRE, "agent");
;         asm volatile("s_waitcnt vmcnt(0)" ::: "memory");
;     }
;     __syncthreads();
; }
.Lli_S:
.Llb_S:
	s_mov_b64 exec, s[4:5]
	s_barrier
	s_mov_b32 s98, 5
	s_branch .LBB0_585

; DI void grid_barrier(unsigned* cnt, unsigned target) {
;     asm volatile("s_waitcnt vmcnt(0) lgkmcnt(0)" ::: "memory");
;     __syncthreads();
;     if (threadIdx.x == 0) {
;         __builtin_amdgcn_fence(__ATOMIC_RELEASE, "agent");
;         asm volatile("s_waitcnt vmcnt(0)" ::: "memory");
;         __hip_atomic_fetch_add(cnt, 1u, __ATOMIC_RELAXED, __HIP_MEMORY_SCOPE_AGENT);
;         while (__hip_atomic_load(cnt, __ATOMIC_RELAXED, __HIP_MEMORY_SCOPE_AGENT) < target) __builtin_amdgcn_s_sleep(2);
;         __builtin_amdgcn_fence(__ATOMIC_ACQUIRE, "agent");
;         asm volatile("s_waitcnt vmcnt(0)" ::: "memory");
;     }
;     __syncthreads();
; }
.Lli_A:
.Llb_A:
	s_mov_b64 exec, s[4:5]
	s_barrier
	s_branch .LBB0_585
